# adds: scalar fma instead of packed fma in DSA indexer, late prefetch of next dynamic-queue unit id in unit epilogues
# speedup vs baseline: 1.2457x; 1.0065x over previous
; #define LAS __attribute__((address_space(3)))
; #define GAS __attribute__((address_space(1)))
; __global__ void __launch_bounds__(512, 2) mega_fwd(Args a) {
;     extern __shared__ __attribute__((aligned(16))) unsigned char lds_raw[];
;     LAS unsigned char* lds = (LAS unsigned char*)lds_raw;
;     LAS unsigned* slot = (LAS unsigned*)(lds + LDS_SLOT);
;     cg::grid_group grid = cg::this_grid();
;     volatile LAS unsigned* bst = (volatile LAS unsigned*)(lds + LDS_SLOT + 16);
;     if (threadIdx.x < 2) bst[threadIdx.x] = 0u;
;     if (blockIdx.x == 0) { GAS u32x4* cz = (GAS u32x4*)(a.ws + WS_CTL); for (int i = threadIdx.x; i < 2048; i += 512) cz[i] = (u32x4){0u, 0u, 0u, 0u}; }
;     __syncthreads();
_Z8mega_fwd4Args:
	s_mov_b32 s101, 0
	s_load_dwordx2 s[96:97], s[0:1], 0x90
	s_add_u32 s26, s0, 0x90
	v_and_b32_e32 v230, 0x3ff, v0
	s_addc_u32 s27, s1, 0
	v_cmp_gt_u32_e32 vcc, 2, v230
	s_and_saveexec_b64 s[6:7], vcc
	v_lshl_add_u32 v1, v230, 2, 0
	v_add_u32_e32 v1, 0x20010, v1
	v_mov_b32_e32 v2, 0
	ds_write_b32 v1, v2
	s_or_b64 exec, exec, s[6:7]
	s_cmp_lg_u32 s2, 0
	v_writelane_b32 v252, s0, 0
	s_load_dwordx2 s[28:29], s[0:1], 0x88
	s_mov_b32 s94, s2
	v_writelane_b32 v252, s1, 1
	s_cbranch_scc1 .LBB0_6
	v_lshlrev_b32_e32 v2, 4, v230
	v_mov_b32_e32 v3, 0
	v_add_u32_e32 v1, 0xfffffe00, v230
	s_waitcnt lgkmcnt(0)
	v_lshl_add_u64 v[6:7], s[28:29], 0, v[2:3]
	s_mov_b64 s[0:1], 0
	v_mov_b32_e32 v2, v3
	v_mov_b32_e32 v4, v3
	v_mov_b32_e32 v5, v3
	s_mov_b64 s[2:3], 0x2000
	s_movk_i32 s4, 0x5ff

; __device__ __forceinline__ int opaque_tid() { int t = (int)threadIdx.x; asm volatile("" : "+v"(t)); return t; }
; #define LAS __attribute__((address_space(3)))
; #define GAS __attribute__((address_space(1)))
; __device__ __forceinline__ unsigned cvtpk(float lo, float hi) { f32x2_t v = {lo, hi}; bf16x2_t b = __builtin_convertvector(v, bf16x2_t); return __builtin_bit_cast(unsigned, b); }
; __device__ __forceinline__ int next_unit(unsigned* ctr, LAS unsigned* slot) {
;     __syncthreads();
;     if (opaque_tid() == 0) *slot = atomicAdd(ctr, 1u);
; template <int MODE> ...
;     ...
;     float inv = 1.f;
;     if (MODE != 1) { const float lt = l + __shfl_xor(l, 32); inv = 1.f / lt; }
;     GAS bf16_t* op = O + (rowbase + q) * OCW + ocol + 4 * hi;
; #pragma unroll
;     for (int g = 0; g < 4; ++g) {
;         u32x2 w0, w1;
;         w0.x = cvtpk(o0[4 * g] * inv, o0[4 * g + 1] * inv); w0.y = cvtpk(o0[4 * g + 2] * inv, o0[4 * g + 3] * inv);
;         w1.x = cvtpk(o1[4 * g] * inv, o1[4 * g + 1] * inv); w1.y = cvtpk(o1[4 * g + 2] * inv, o1[4 * g + 3] * inv);
;         *(GAS u32x2*)(op + 8 * g) = w0; *(GAS u32x2*)(op + 32 + 8 * g) = w1;
;     }
.LBB0_339:
	v_cmp_eq_u32_e64 s[72:73], 0, v230
	s_and_saveexec_b64 s[74:75], s[72:73]
	s_cbranch_execz .Lupf_skip1
	v_readlane_b32 s70, v252, 53
	v_readlane_b32 s71, v252, 54
	v_mov_b32_e32 v250, 0
	s_nop 3
	global_atomic_add v251, v250, v223, s[70:71] sc0
	s_mov_b32 s101, 1
.Lupf_skip1:
	s_or_b64 exec, exec, s[74:75]
	ds_bpermute_b32 v1, v109, v114
	s_movk_i32 s4, 0x300
	v_mov_b32_e32 v39, v0
	s_waitcnt lgkmcnt(0)
	v_add_f32_e32 v1, v114, v1
	v_div_scale_f32 v34, s[0:1], v1, v1, 1.0
	v_rcp_f32_e32 v35, v34
	v_readlane_b32 s0, v252, 62
	v_readlane_b32 s1, v252, 63
	v_fma_f32 v36, -v34, v35, 1.0
	v_fmac_f32_e32 v35, v36, v35
	v_div_scale_f32 v36, vcc, 1.0, v1, 1.0
	v_mul_f32_e32 v37, v36, v35
	v_fma_f32 v38, -v34, v37, v36
	v_fmac_f32_e32 v37, v38, v35
	v_fma_f32 v34, -v34, v37, v36
	v_div_fmas_f32 v34, v34, v35, v37
	v_mov_b64_e32 v[36:37], s[0:1]
	v_mad_u64_u32 v[36:37], s[0:1], v100, s4, v[36:37]
	v_div_fixup_f32 v34, v34, v1, 1.0
	v_mad_i32_i24 v37, v101, s4, v37
	v_lshl_add_u64 v[36:37], s[2:3], 1, v[36:37]
	v_lshlrev_b32_e32 v38, 1, v103
	v_pk_mul_f32 v[18:19], v[18:19], v[34:35] op_sel_hi:[1,0]
	v_pk_mul_f32 v[20:21], v[20:21], v[34:35] op_sel_hi:[1,0]
	v_pk_mul_f32 v[2:3], v[2:3], v[34:35] op_sel_hi:[1,0]
	v_pk_mul_f32 v[4:5], v[4:5], v[34:35] op_sel_hi:[1,0]
	v_lshl_add_u64 v[36:37], v[36:37], 0, v[38:39]
	v_cvt_pk_bf16_f32 v18, v18, v19
	v_cvt_pk_bf16_f32 v19, v20, v21
	v_cvt_pk_bf16_f32 v2, v2, v3
	v_cvt_pk_bf16_f32 v3, v4, v5
	global_store_dwordx2 v[36:37], v[18:19], off
	global_store_dwordx2 v[36:37], v[2:3], off offset:64
	v_pk_mul_f32 v[2:3], v[22:23], v[34:35] op_sel_hi:[1,0]
	v_pk_mul_f32 v[4:5], v[24:25], v[34:35] op_sel_hi:[1,0]
	v_cvt_pk_bf16_f32 v2, v2, v3
	v_cvt_pk_bf16_f32 v3, v4, v5
	v_pk_mul_f32 v[4:5], v[6:7], v[34:35] op_sel_hi:[1,0]
	v_pk_mul_f32 v[6:7], v[8:9], v[34:35] op_sel_hi:[1,0]
	v_cvt_pk_bf16_f32 v4, v4, v5
	v_cvt_pk_bf16_f32 v5, v6, v7
	global_store_dwordx2 v[36:37], v[2:3], off offset:16
	global_store_dwordx2 v[36:37], v[4:5], off offset:80
	v_pk_mul_f32 v[2:3], v[26:27], v[34:35] op_sel_hi:[1,0]
	v_pk_mul_f32 v[4:5], v[28:29], v[34:35] op_sel_hi:[1,0]
	v_cvt_pk_bf16_f32 v2, v2, v3
	v_cvt_pk_bf16_f32 v3, v4, v5
	v_pk_mul_f32 v[4:5], v[10:11], v[34:35] op_sel_hi:[1,0]
	v_pk_mul_f32 v[6:7], v[12:13], v[34:35] op_sel_hi:[1,0]
	v_cvt_pk_bf16_f32 v4, v4, v5
	v_cvt_pk_bf16_f32 v5, v6, v7
	global_store_dwordx2 v[36:37], v[2:3], off offset:32
	global_store_dwordx2 v[36:37], v[4:5], off offset:96
	v_pk_mul_f32 v[2:3], v[30:31], v[34:35] op_sel_hi:[1,0]
	v_pk_mul_f32 v[4:5], v[32:33], v[34:35] op_sel_hi:[1,0]
	v_cvt_pk_bf16_f32 v2, v2, v3
	v_cvt_pk_bf16_f32 v3, v4, v5
	v_pk_mul_f32 v[4:5], v[14:15], v[34:35] op_sel_hi:[1,0]
	v_pk_mul_f32 v[6:7], v[16:17], v[34:35] op_sel_hi:[1,0]
	v_cvt_pk_bf16_f32 v4, v4, v5
	v_cvt_pk_bf16_f32 v5, v6, v7
	global_store_dwordx2 v[36:37], v[2:3], off offset:48
	global_store_dwordx2 v[36:37], v[4:5], off offset:112

; __device__ __forceinline__ int opaque_tid() { int t = (int)threadIdx.x; asm volatile("" : "+v"(t)); return t; }
; #define LAS __attribute__((address_space(3)))
; __device__ __forceinline__ int next_unit(unsigned* ctr, LAS unsigned* slot) {
;     __syncthreads();
;     if (opaque_tid() == 0) *slot = atomicAdd(ctr, 1u);
;     __syncthreads();
;     return __builtin_amdgcn_readfirstlane((int)*slot);
.LBB0_342:
	v_mov_b32_e32 v1, v230
	s_barrier
	s_nop 0
	v_cmp_eq_u32_e32 vcc, 0, v1
	s_and_saveexec_b64 s[0:1], vcc
	s_cbranch_execz .LBB0_344
	s_cmp_lg_u32 s101, 0
	s_cbranch_scc1 .Lupf_have_p2
	v_readlane_b32 s2, v252, 53
	v_readlane_b32 s3, v252, 54
	s_nop 1
	v_mov_b64_e32 v[2:3], s[2:3]
	flat_atomic_add v1, v[2:3], v223 sc0
	s_branch .Lupf_join_p2
.Lupf_have_p2:
	s_mov_b32 s101, 0
	s_waitcnt vmcnt(0)
	v_mov_b32_e32 v1, v251
.Lupf_join_p2:
	v_readlane_b32 s2, v252, 28
	s_nop 1
	v_mov_b32_e32 v2, s2
	s_waitcnt vmcnt(0) lgkmcnt(0)
	ds_write_b32 v2, v1

; #define GAS __attribute__((address_space(1)))
; __device__ __forceinline__ void select_unit(LAS unsigned char* lds, const GAS bf16_t* __restrict__ HA, const GAS float* __restrict__ IW, int b, int qc, GAS float* __restrict__ scr, GAS unsigned long long* __restrict__ MB) {
;     ...
; #pragma unroll
;                     for (int hh = 0; hh < 8; ++hh) {
;                         f32x4 acc = __builtin_amdgcn_mfma_f32_16x16x32_bf16(k0, iqf[hh][0], (f32x4){0.f, 0.f, 0.f, 0.f}, 0, 0, 0);
;                         acc = __builtin_amdgcn_mfma_f32_16x16x32_bf16(k1, iqf[hh][1], acc, 0, 0, 0);
; #pragma unroll
;                         for (int r = 0; r < 4; ++r) sc[r] += iwv[hh] * fmaxf(acc[r], 0.f);
;                     }
;                     *(GAS f32x4*)(scr + (size_t)ql * SEQ + kb * 16 + 4 * lg) = sc;
.LBB0_360:
	s_cmp_ge_i32 s13, s7
	s_cbranch_scc1 .LBB0_362
	ds_read_b128 v[94:97], v119
	ds_read_b128 v[90:93], v119 offset:64
	s_waitcnt lgkmcnt(1)
	v_mfma_f32_16x16x32_bf16 v[148:151], v[94:97], v[82:85], 0
	v_mfma_f32_16x16x32_bf16 v[156:159], v[94:97], v[30:33], 0
	v_mfma_f32_16x16x32_bf16 v[172:175], v[94:97], v[38:41], 0
	v_mfma_f32_16x16x32_bf16 v[182:185], v[94:97], v[46:49], 0
	v_mfma_f32_16x16x32_bf16 v[186:189], v[94:97], v[54:57], 0
	v_mfma_f32_16x16x32_bf16 v[190:193], v[94:97], v[62:65], 0
	v_mfma_f32_16x16x32_bf16 v[198:201], v[94:97], v[70:73], 0
	v_mfma_f32_16x16x32_bf16 v[202:205], v[94:97], v[78:81], 0
	s_waitcnt lgkmcnt(0)
	v_mfma_f32_16x16x32_bf16 v[148:151], v[90:93], v[26:29], v[148:151]
	v_mfma_f32_16x16x32_bf16 v[156:159], v[90:93], v[34:37], v[156:159]
	v_mfma_f32_16x16x32_bf16 v[172:175], v[90:93], v[42:45], v[172:175]
	v_mfma_f32_16x16x32_bf16 v[182:185], v[90:93], v[50:53], v[182:185]
	v_mfma_f32_16x16x32_bf16 v[186:189], v[90:93], v[58:61], v[186:189]
	v_mfma_f32_16x16x32_bf16 v[190:193], v[90:93], v[66:69], v[190:193]
	v_mfma_f32_16x16x32_bf16 v[198:201], v[90:93], v[74:77], v[198:201]
	v_mfma_f32_16x16x32_bf16 v[202:205], v[90:93], v[86:89], v[202:205]
	s_add_i32 s14, s10, s12
	s_ashr_i32 s15, s14, 31
	v_lshl_add_u64 v[94:95], s[14:15], 2, v[100:101]
	v_max_f32_e32 v148, 0, v148
	v_max_f32_e32 v149, 0, v149
	v_max_f32_e32 v150, 0, v150
	v_max_f32_e32 v151, 0, v151
	v_fma_f32 v90, v102, v148, 0
	v_fma_f32 v91, v103, v149, 0
	v_fma_f32 v92, v102, v150, 0
	v_fma_f32 v93, v103, v151, 0
	v_max_f32_e32 v156, 0, v156
	v_max_f32_e32 v157, 0, v157
	v_max_f32_e32 v158, 0, v158
	v_max_f32_e32 v159, 0, v159
	v_fmac_f32_e32 v90, v22, v156
	v_fmac_f32_e32 v91, v23, v157
	v_fmac_f32_e32 v92, v22, v158
	v_fmac_f32_e32 v93, v23, v159
	v_max_f32_e32 v172, 0, v172
	v_max_f32_e32 v173, 0, v173
	v_max_f32_e32 v174, 0, v174
	v_max_f32_e32 v175, 0, v175
	v_fmac_f32_e32 v90, v104, v172
	v_fmac_f32_e32 v91, v105, v173
	v_fmac_f32_e32 v92, v104, v174
	v_fmac_f32_e32 v93, v105, v175
	v_max_f32_e32 v182, 0, v182
	v_max_f32_e32 v183, 0, v183
	v_max_f32_e32 v184, 0, v184
	v_max_f32_e32 v185, 0, v185
	v_fmac_f32_e32 v90, v24, v182
	v_fmac_f32_e32 v91, v25, v183
	v_fmac_f32_e32 v92, v24, v184
	v_fmac_f32_e32 v93, v25, v185
	v_max_f32_e32 v186, 0, v186
	v_max_f32_e32 v187, 0, v187
	v_max_f32_e32 v188, 0, v188
	v_max_f32_e32 v189, 0, v189
	v_fmac_f32_e32 v90, v106, v186
	v_fmac_f32_e32 v91, v107, v187
	v_fmac_f32_e32 v92, v106, v188
	v_fmac_f32_e32 v93, v107, v189
	v_max_f32_e32 v190, 0, v190
	v_max_f32_e32 v191, 0, v191
	v_max_f32_e32 v192, 0, v192
	v_max_f32_e32 v193, 0, v193
	v_fmac_f32_e32 v90, v18, v190
	v_fmac_f32_e32 v91, v19, v191
	v_fmac_f32_e32 v92, v18, v192
	v_fmac_f32_e32 v93, v19, v193
	v_max_f32_e32 v198, 0, v198
	v_max_f32_e32 v199, 0, v199
	v_max_f32_e32 v200, 0, v200
	v_max_f32_e32 v201, 0, v201
	v_fmac_f32_e32 v90, v108, v198
	v_fmac_f32_e32 v91, v109, v199
	v_fmac_f32_e32 v92, v108, v200
	v_fmac_f32_e32 v93, v109, v201
	v_max_f32_e32 v202, 0, v202
	v_max_f32_e32 v203, 0, v203
	v_max_f32_e32 v204, 0, v204
	v_max_f32_e32 v205, 0, v205
	v_fmac_f32_e32 v90, v20, v202
	v_fmac_f32_e32 v91, v21, v203
	v_fmac_f32_e32 v92, v20, v204
	v_fmac_f32_e32 v93, v21, v205
	global_store_dwordx4 v[94:95], v[90:93], off
.LBB0_362:
	s_add_i32 s14, s13, 2
	s_cmp_ge_i32 s14, s7
	s_cbranch_scc1 .LBB0_359
	ds_read_b128 v[94:97], v119 offset:4608
	ds_read_b128 v[90:93], v119 offset:4672
	s_waitcnt lgkmcnt(1)
	v_mfma_f32_16x16x32_bf16 v[148:151], v[94:97], v[82:85], 0
	v_mfma_f32_16x16x32_bf16 v[156:159], v[94:97], v[30:33], 0
	v_mfma_f32_16x16x32_bf16 v[172:175], v[94:97], v[38:41], 0
	v_mfma_f32_16x16x32_bf16 v[182:185], v[94:97], v[46:49], 0
	v_mfma_f32_16x16x32_bf16 v[186:189], v[94:97], v[54:57], 0
	v_mfma_f32_16x16x32_bf16 v[190:193], v[94:97], v[62:65], 0
	v_mfma_f32_16x16x32_bf16 v[198:201], v[94:97], v[70:73], 0
	v_mfma_f32_16x16x32_bf16 v[202:205], v[94:97], v[78:81], 0
	s_waitcnt lgkmcnt(0)
	v_mfma_f32_16x16x32_bf16 v[148:151], v[90:93], v[26:29], v[148:151]
	v_mfma_f32_16x16x32_bf16 v[156:159], v[90:93], v[34:37], v[156:159]
	v_mfma_f32_16x16x32_bf16 v[172:175], v[90:93], v[42:45], v[172:175]
	v_mfma_f32_16x16x32_bf16 v[182:185], v[90:93], v[50:53], v[182:185]
	v_mfma_f32_16x16x32_bf16 v[186:189], v[90:93], v[58:61], v[186:189]
	v_mfma_f32_16x16x32_bf16 v[190:193], v[90:93], v[66:69], v[190:193]
	v_mfma_f32_16x16x32_bf16 v[198:201], v[90:93], v[74:77], v[198:201]
	v_mfma_f32_16x16x32_bf16 v[202:205], v[90:93], v[86:89], v[202:205]
	s_add_i32 s14, s10, s12
	s_add_i32 s14, s14, 32
	s_ashr_i32 s15, s14, 31
	v_lshl_add_u64 v[94:95], s[14:15], 2, v[100:101]
	v_max_f32_e32 v148, 0, v148
	v_max_f32_e32 v149, 0, v149
	v_max_f32_e32 v150, 0, v150
	v_max_f32_e32 v151, 0, v151
	v_fma_f32 v90, v102, v148, 0
	v_fma_f32 v91, v103, v149, 0
	v_fma_f32 v92, v102, v150, 0
	v_fma_f32 v93, v103, v151, 0
	v_max_f32_e32 v156, 0, v156
	v_max_f32_e32 v157, 0, v157
	v_max_f32_e32 v158, 0, v158
	v_max_f32_e32 v159, 0, v159
	v_fmac_f32_e32 v90, v22, v156
	v_fmac_f32_e32 v91, v23, v157
	v_fmac_f32_e32 v92, v22, v158
	v_fmac_f32_e32 v93, v23, v159
	v_max_f32_e32 v172, 0, v172
	v_max_f32_e32 v173, 0, v173
	v_max_f32_e32 v174, 0, v174
	v_max_f32_e32 v175, 0, v175
	v_fmac_f32_e32 v90, v104, v172
	v_fmac_f32_e32 v91, v105, v173
	v_fmac_f32_e32 v92, v104, v174
	v_fmac_f32_e32 v93, v105, v175
	v_max_f32_e32 v182, 0, v182
	v_max_f32_e32 v183, 0, v183
	v_max_f32_e32 v184, 0, v184
	v_max_f32_e32 v185, 0, v185
	v_fmac_f32_e32 v90, v24, v182
	v_fmac_f32_e32 v91, v25, v183
	v_fmac_f32_e32 v92, v24, v184
	v_fmac_f32_e32 v93, v25, v185
	v_max_f32_e32 v186, 0, v186
	v_max_f32_e32 v187, 0, v187
	v_max_f32_e32 v188, 0, v188
	v_max_f32_e32 v189, 0, v189
	v_fmac_f32_e32 v90, v106, v186
	v_fmac_f32_e32 v91, v107, v187
	v_fmac_f32_e32 v92, v106, v188
	v_fmac_f32_e32 v93, v107, v189
	v_max_f32_e32 v190, 0, v190
	v_max_f32_e32 v191, 0, v191
	v_max_f32_e32 v192, 0, v192
	v_max_f32_e32 v193, 0, v193
	v_fmac_f32_e32 v90, v18, v190
	v_fmac_f32_e32 v91, v19, v191
	v_fmac_f32_e32 v92, v18, v192
	v_fmac_f32_e32 v93, v19, v193
	v_max_f32_e32 v198, 0, v198
	v_max_f32_e32 v199, 0, v199
	v_max_f32_e32 v200, 0, v200
	v_max_f32_e32 v201, 0, v201
	v_fmac_f32_e32 v90, v108, v198
	v_fmac_f32_e32 v91, v109, v199
	v_fmac_f32_e32 v92, v108, v200
	v_fmac_f32_e32 v93, v109, v201
	v_max_f32_e32 v202, 0, v202
	v_max_f32_e32 v203, 0, v203
	v_max_f32_e32 v204, 0, v204
	v_max_f32_e32 v205, 0, v205
	v_fmac_f32_e32 v90, v20, v202
	v_fmac_f32_e32 v91, v21, v203
	v_fmac_f32_e32 v92, v20, v204
	v_fmac_f32_e32 v93, v21, v205
	global_store_dwordx4 v[94:95], v[90:93], off
	s_branch .LBB0_359

; #define GAS __attribute__((address_space(1)))
; __device__ __forceinline__ unsigned cvtpk(float lo, float hi) { f32x2_t v = {lo, hi}; bf16x2_t b = __builtin_convertvector(v, bf16x2_t); return __builtin_bit_cast(unsigned, b); }
; template <int MODE> ...
;     ...
;     float inv = 1.f;
;     if (MODE != 1) { const float lt = l + __shfl_xor(l, 32); inv = 1.f / lt; }
;     GAS bf16_t* op = O + (rowbase + q) * OCW + ocol + 4 * hi;
; #pragma unroll
;     for (int g = 0; g < 4; ++g) {
;         u32x2 w0, w1;
;         w0.x = cvtpk(o0[4 * g] * inv, o0[4 * g + 1] * inv); w0.y = cvtpk(o0[4 * g + 2] * inv, o0[4 * g + 3] * inv);
;         w1.x = cvtpk(o1[4 * g] * inv, o1[4 * g + 1] * inv); w1.y = cvtpk(o1[4 * g + 2] * inv, o1[4 * g + 3] * inv);
;         *(GAS u32x2*)(op + 8 * g) = w0; *(GAS u32x2*)(op + 32 + 8 * g) = w1;
;     }
.Lupf_skip2:
	s_or_b64 exec, exec, s[74:75]
	v_readlane_b32 s0, v254, 4
	v_readlane_b32 s1, v254, 5
	s_movk_i32 s2, 0x300
	v_lshlrev_b32_e32 v36, 1, v131
	v_mov_b64_e32 v[34:35], s[0:1]
	v_mad_u64_u32 v[34:35], s[0:1], v128, s2, v[34:35]
	v_mad_i32_i24 v35, v129, s2, v35
	v_lshl_add_u64 v[34:35], v[34:35], 0, s[88:89]
	v_mov_b32_e32 v37, v0
	v_lshl_add_u64 v[34:35], v[34:35], 0, v[36:37]
	v_cvt_pk_bf16_f32 v18, v18, v19
	v_cvt_pk_bf16_f32 v19, v20, v21
	v_cvt_pk_bf16_f32 v2, v2, v3
	v_cvt_pk_bf16_f32 v3, v4, v5
	global_store_dwordx2 v[34:35], v[18:19], off
	global_store_dwordx2 v[34:35], v[2:3], off offset:64
	v_cvt_pk_bf16_f32 v2, v22, v23
	v_cvt_pk_bf16_f32 v3, v24, v25
	v_cvt_pk_bf16_f32 v4, v6, v7
	v_cvt_pk_bf16_f32 v5, v8, v9
	global_store_dwordx2 v[34:35], v[2:3], off offset:16
	global_store_dwordx2 v[34:35], v[4:5], off offset:80
	v_cvt_pk_bf16_f32 v2, v26, v27
	v_cvt_pk_bf16_f32 v3, v28, v29
	v_cvt_pk_bf16_f32 v4, v10, v11
	v_cvt_pk_bf16_f32 v5, v12, v13
	global_store_dwordx2 v[34:35], v[2:3], off offset:32
	global_store_dwordx2 v[34:35], v[4:5], off offset:96
	v_cvt_pk_bf16_f32 v2, v30, v31
	v_cvt_pk_bf16_f32 v3, v32, v33
	v_cvt_pk_bf16_f32 v4, v14, v15
	v_cvt_pk_bf16_f32 v5, v16, v17
	global_store_dwordx2 v[34:35], v[2:3], off offset:48
	global_store_dwordx2 v[34:35], v[4:5], off offset:112
	s_mov_b32 s88, 0xefa18f08
	s_cbranch_execnz .LBB0_340
	s_branch .LBB0_811

; #define GAS __attribute__((address_space(1)))
; __device__ __forceinline__ unsigned cvtpk(float lo, float hi) { f32x2_t v = {lo, hi}; bf16x2_t b = __builtin_convertvector(v, bf16x2_t); return __builtin_bit_cast(unsigned, b); }
; template <int MODE> ...
;     ...
;     float inv = 1.f;
;     if (MODE != 1) { const float lt = l + __shfl_xor(l, 32); inv = 1.f / lt; }
;     GAS bf16_t* op = O + (rowbase + q) * OCW + ocol + 4 * hi;
; #pragma unroll
;     for (int g = 0; g < 4; ++g) {
;         u32x2 w0, w1;
;         w0.x = cvtpk(o0[4 * g] * inv, o0[4 * g + 1] * inv); w0.y = cvtpk(o0[4 * g + 2] * inv, o0[4 * g + 3] * inv);
;         w1.x = cvtpk(o1[4 * g] * inv, o1[4 * g + 1] * inv); w1.y = cvtpk(o1[4 * g + 2] * inv, o1[4 * g + 3] * inv);
;         *(GAS u32x2*)(op + 8 * g) = w0; *(GAS u32x2*)(op + 32 + 8 * g) = w1;
;     }
; __global__ void __launch_bounds__(512, 2) mega_fwd(Args a) {
;     ...
;             for (;;) {
;                 const int u = next_unit(ctr, slot); if (u >= 1280) break;
;                 const int qb = 7 - u / 160, e = u % 160, b = e / 5, h = e % 5;
;                 attn_unit<2>(lds, HA, b, qb, 2112 + h * 64, 2432, 2496, OC + 2 * OC_STRIDE, h * 64, (const GAS float*)nullptr, 0.f, MB);
.LBB0_914:
	v_cmp_eq_u32_e64 s[72:73], 0, v230
	s_and_saveexec_b64 s[74:75], s[72:73]
	s_cbranch_execz .Lupf_skip3
	v_mov_b32_e32 v250, 0
	s_nop 0
	global_atomic_add v251, v250, v223, s[0:1] offset:256 sc0
	s_mov_b32 s101, 1
.Lupf_skip3:
	s_or_b64 exec, exec, s[74:75]
	v_and_b32_e32 v34, 64, v224
	v_xor_b32_e32 v1, 32, v224
	v_add_u32_e32 v34, 64, v34
	v_cmp_lt_i32_e32 vcc, v1, v34
	v_mov_b32_e32 v39, v0
	s_nop 0
	v_cndmask_b32_e32 v1, v224, v1, vcc
	v_lshlrev_b32_e32 v1, 2, v1
	ds_bpermute_b32 v1, v1, v111
	s_waitcnt lgkmcnt(0)
	v_add_f32_e32 v1, v111, v1
	v_div_scale_f32 v34, s[10:11], v1, v1, 1.0
	v_rcp_f32_e32 v35, v34
	s_nop 0
	v_fma_f32 v36, -v34, v35, 1.0
	v_fmac_f32_e32 v35, v36, v35
	v_div_scale_f32 v36, vcc, 1.0, v1, 1.0
	v_mul_f32_e32 v37, v36, v35
	v_fma_f32 v38, -v34, v37, v36
	v_fmac_f32_e32 v37, v38, v35
	v_fma_f32 v34, -v34, v37, v36
	v_div_fmas_f32 v34, v34, v35, v37
	v_mov_b64_e32 v[36:37], s[6:7]
	v_mad_u64_u32 v[36:37], s[10:11], v98, s52, v[36:37]
	v_div_fixup_f32 v34, v34, v1, 1.0
	v_mad_i32_i24 v37, v99, s52, v37
	v_lshl_add_u64 v[36:37], s[8:9], 1, v[36:37]
	v_lshlrev_b32_e32 v38, 1, v100
	v_pk_mul_f32 v[18:19], v[18:19], v[34:35] op_sel_hi:[1,0]
	v_pk_mul_f32 v[20:21], v[20:21], v[34:35] op_sel_hi:[1,0]
	v_pk_mul_f32 v[2:3], v[2:3], v[34:35] op_sel_hi:[1,0]
	v_pk_mul_f32 v[4:5], v[4:5], v[34:35] op_sel_hi:[1,0]
	v_lshl_add_u64 v[36:37], v[36:37], 0, v[38:39]
	v_cvt_pk_bf16_f32 v18, v18, v19
	v_cvt_pk_bf16_f32 v19, v20, v21
	v_cvt_pk_bf16_f32 v2, v2, v3
	v_cvt_pk_bf16_f32 v3, v4, v5
	global_store_dwordx2 v[36:37], v[18:19], off
	global_store_dwordx2 v[36:37], v[2:3], off offset:64
	v_pk_mul_f32 v[2:3], v[22:23], v[34:35] op_sel_hi:[1,0]
	v_pk_mul_f32 v[4:5], v[24:25], v[34:35] op_sel_hi:[1,0]
	v_cvt_pk_bf16_f32 v2, v2, v3
	v_cvt_pk_bf16_f32 v3, v4, v5
	v_pk_mul_f32 v[4:5], v[6:7], v[34:35] op_sel_hi:[1,0]
	v_pk_mul_f32 v[6:7], v[8:9], v[34:35] op_sel_hi:[1,0]
	v_cvt_pk_bf16_f32 v4, v4, v5
	v_cvt_pk_bf16_f32 v5, v6, v7
	global_store_dwordx2 v[36:37], v[2:3], off offset:16
	global_store_dwordx2 v[36:37], v[4:5], off offset:80
	v_pk_mul_f32 v[2:3], v[26:27], v[34:35] op_sel_hi:[1,0]
	v_pk_mul_f32 v[4:5], v[28:29], v[34:35] op_sel_hi:[1,0]
	v_cvt_pk_bf16_f32 v2, v2, v3
	v_cvt_pk_bf16_f32 v3, v4, v5
	v_pk_mul_f32 v[4:5], v[10:11], v[34:35] op_sel_hi:[1,0]
	v_pk_mul_f32 v[6:7], v[12:13], v[34:35] op_sel_hi:[1,0]
	v_cvt_pk_bf16_f32 v4, v4, v5
	v_cvt_pk_bf16_f32 v5, v6, v7
	global_store_dwordx2 v[36:37], v[2:3], off offset:32
	global_store_dwordx2 v[36:37], v[4:5], off offset:96
	v_pk_mul_f32 v[2:3], v[30:31], v[34:35] op_sel_hi:[1,0]
	v_pk_mul_f32 v[4:5], v[32:33], v[34:35] op_sel_hi:[1,0]
	v_cvt_pk_bf16_f32 v2, v2, v3
	v_cvt_pk_bf16_f32 v3, v4, v5
	v_pk_mul_f32 v[4:5], v[14:15], v[34:35] op_sel_hi:[1,0]
	v_pk_mul_f32 v[6:7], v[16:17], v[34:35] op_sel_hi:[1,0]
	s_mov_b64 s[8:9], 0
	v_cvt_pk_bf16_f32 v4, v4, v5
	v_cvt_pk_bf16_f32 v5, v6, v7
	global_store_dwordx2 v[36:37], v[2:3], off offset:48
	global_store_dwordx2 v[36:37], v[4:5], off offset:112

; __device__ __forceinline__ int opaque_tid() { int t = (int)threadIdx.x; asm volatile("" : "+v"(t)); return t; }
; #define LAS __attribute__((address_space(3)))
; __device__ __forceinline__ int next_unit(unsigned* ctr, LAS unsigned* slot) {
;     __syncthreads();
;     if (opaque_tid() == 0) *slot = atomicAdd(ctr, 1u);
;     __syncthreads();
;     return __builtin_amdgcn_readfirstlane((int)*slot);
.LBB0_916:
	v_mov_b32_e32 v1, v230
	s_barrier
	s_nop 0
	v_cmp_eq_u32_e32 vcc, 0, v1
	s_and_saveexec_b64 s[8:9], vcc
	s_cbranch_execz .LBB0_918
	s_cmp_lg_u32 s101, 0
	s_cbranch_scc1 .Lupf_have_p3
	v_mov_b64_e32 v[2:3], s[0:1]
	flat_atomic_add v1, v[2:3], v223 offset:256 sc0
	s_branch .Lupf_join_p3

; __device__ __forceinline__ int opaque_tid() { int t = (int)threadIdx.x; asm volatile("" : "+v"(t)); return t; }
; __device__ __forceinline__ int next_unit(unsigned* ctr, LAS unsigned* slot) {
;     ...
;     if (opaque_tid() == 0) *slot = atomicAdd(ctr, 1u);
;     __syncthreads();
;     return __builtin_amdgcn_readfirstlane((int)*slot);
.Lupf_join_p3:
	v_readlane_b32 s10, v252, 28
	s_nop 1
	v_mov_b32_e32 v2, s10
	s_waitcnt vmcnt(0) lgkmcnt(0)
	ds_write_b32 v2, v1

; __global__ void __launch_bounds__(512, 2) mega_fwd(Args a) {
	.amdhsa_kernel _Z8mega_fwd4Args
		.amdhsa_group_segment_fixed_size 0
		.amdhsa_private_segment_fixed_size 0
		.amdhsa_kernarg_size 400
		.amdhsa_user_sgpr_count 2
		.amdhsa_user_sgpr_dispatch_ptr 0
		.amdhsa_user_sgpr_queue_ptr 0
		.amdhsa_user_sgpr_kernarg_segment_ptr 1
		.amdhsa_user_sgpr_dispatch_id 0
		.amdhsa_user_sgpr_kernarg_preload_length 0
		.amdhsa_user_sgpr_kernarg_preload_offset 0
		.amdhsa_user_sgpr_private_segment_size 0
		.amdhsa_uses_dynamic_stack 0
		.amdhsa_enable_private_segment 0
		.amdhsa_system_sgpr_workgroup_id_x 1
		.amdhsa_system_sgpr_workgroup_id_y 0
		.amdhsa_system_sgpr_workgroup_id_z 0
		.amdhsa_system_sgpr_workgroup_info 0
		.amdhsa_system_vgpr_workitem_id 2
		.amdhsa_next_free_vgpr 256
		.amdhsa_next_free_sgpr 102
		.amdhsa_accum_offset 256
		.amdhsa_reserve_vcc 1
		.amdhsa_float_round_mode_32 0
		.amdhsa_float_round_mode_16_64 0
		.amdhsa_float_denorm_mode_32 3
		.amdhsa_float_denorm_mode_16_64 3
		.amdhsa_dx10_clamp 1
		.amdhsa_ieee_mode 1
		.amdhsa_fp16_overflow 0
		.amdhsa_tg_split 0
		.amdhsa_exception_fp_ieee_invalid_op 0
		.amdhsa_exception_fp_denorm_src 0
		.amdhsa_exception_fp_ieee_div_zero 0
		.amdhsa_exception_fp_ieee_overflow 0
		.amdhsa_exception_fp_ieee_underflow 0
		.amdhsa_exception_fp_ieee_inexact 0
		.amdhsa_exception_int_div_zero 0
	.end_amdhsa_kernel

; __global__ void __launch_bounds__(512, 2) mega_fwd(Args a) {
.Lfunc_end0:
	.size	_Z8mega_fwd4Args, .Lfunc_end0-_Z8mega_fwd4Args
	.set _Z8mega_fwd4Args.num_vgpr, 256
	.set _Z8mega_fwd4Args.num_agpr, 0
	.set _Z8mega_fwd4Args.numbered_sgpr, 102
	.set _Z8mega_fwd4Args.num_named_barrier, 0
	.set _Z8mega_fwd4Args.private_seg_size, 0
	.set _Z8mega_fwd4Args.uses_vcc, 1
	.set _Z8mega_fwd4Args.uses_flat_scratch, 0
	.set _Z8mega_fwd4Args.has_dyn_sized_stack, 0
	.set _Z8mega_fwd4Args.has_recursion, 0
	.set _Z8mega_fwd4Args.has_indirect_call, 0

; __global__ void __launch_bounds__(512, 2) mega_fwd(Args a) {
amdhsa.kernels:
  - .agpr_count:     0
    .args:
      - .offset:         0
        .size:           144
        .value_kind:     by_value
      - .offset:         144
        .size:           4
        .value_kind:     hidden_block_count_x
      - .offset:         148
        .size:           4
        .value_kind:     hidden_block_count_y
      - .offset:         152
        .size:           4
        .value_kind:     hidden_block_count_z
      - .offset:         156
        .size:           2
        .value_kind:     hidden_group_size_x
      - .offset:         158
        .size:           2
        .value_kind:     hidden_group_size_y
      - .offset:         160
        .size:           2
        .value_kind:     hidden_group_size_z
      - .offset:         162
        .size:           2
        .value_kind:     hidden_remainder_x
      - .offset:         164
        .size:           2
        .value_kind:     hidden_remainder_y
      - .offset:         166
        .size:           2
        .value_kind:     hidden_remainder_z
      - .offset:         184
        .size:           8
        .value_kind:     hidden_global_offset_x
      - .offset:         192
        .size:           8
        .value_kind:     hidden_global_offset_y
      - .offset:         200
        .size:           8
        .value_kind:     hidden_global_offset_z
      - .offset:         208
        .size:           2
        .value_kind:     hidden_grid_dims
      - .offset:         232
        .size:           8
        .value_kind:     hidden_multigrid_sync_arg
      - .offset:         264
        .size:           4
        .value_kind:     hidden_dynamic_lds_size
    .group_segment_fixed_size: 0
    .kernarg_segment_align: 8
    .kernarg_segment_size: 400
    .language:       OpenCL C
    .language_version:
      - 2
      - 0
    .max_flat_workgroup_size: 512
    .name:           _Z8mega_fwd4Args
    .private_segment_fixed_size: 0
    .sgpr_count:     108
    .sgpr_spill_count: 336
    .symbol:         _Z8mega_fwd4Args.kd
    .uniform_work_group_size: 1
    .uses_dynamic_stack: false
    .vgpr_count:     256
    .vgpr_spill_count: 0
    .wavefront_size: 64
